# v32: v25 + conv tap loop 8 rows per pass + epilogue stores deferred by two sites
# speedup vs baseline: 1.0043x; 1.0043x over previous
; __device__ __forceinline__ unsigned cvt_pk_bf16(float lo, float hi) { unsigned r; asm volatile("v_cvt_pk_bf16_f32 %0, %1, %2" : "=v"(r) : "v"(lo), "v"(hi)); return r; }
; __device__ __forceinline__ float relu_sq(float x) { float r; asm volatile("v_max_f32 %0, 0, %1" : "=v"(r) : "v"(x)); return r * r; }
;     __device__ __forceinline__ void operator()(const f32x4 (&acc)[2][2][4][2], const Unit& u, int wr, int wc, int fr, int fq) const {
;     ...
;             for (int m = 0; m < 4; ++m) { const int row_ = row0 + ai * HALF + m * 16; bf16_t* rowp = O + (size_t)(row_ >> 11) * gs + (size_t)(row_ & 2047) * ldc + col0; const float sc = rs ? rs[row0 + ai * HALF + m * 16] : 1.f;
; #pragma unroll
;                 for (int bj = 0; bj < 2; ++bj) { f32x4 v0 = acc[ai][bj][m][0] * sc, v1 = acc[ai][bj][m][1] * sc;
;                     if (ACT == 1) {
; #pragma unroll
;                         for (int e = 0; e < 4; ++e) { v0[e] = relu_sq(v0[e]); v1[e] = relu_sq(v1[e]); } }
;                     u32x4 w; w.x = cvt_pk_bf16(v0[0], v0[1]); w.y = cvt_pk_bf16(v0[2], v0[3]); w.z = cvt_pk_bf16(v1[0], v1[1]); w.w = cvt_pk_bf16(v1[2], v1[3]);
;                     *(u32x4*)(rowp + bj * HALF) = w; } }
.LBB0_40:
	s_ashr_i32 s13, s13, 11
	s_mul_hi_i32 s19, s13, 0x1040000
	s_mul_i32 s13, s13, 0x1040000
	v_and_b32_e32 v128, 0x7cf, v150
	s_add_u32 s18, s64, s13
	v_mul_u32_u24_e32 v128, 0x1040, v128
	s_nop 0
	v_pk_mul_f32 v[124:125], v[124:125], v[200:201] op_sel_hi:[1,0]
	v_pk_mul_f32 v[120:121], v[120:121], v[200:201] op_sel_hi:[1,0]
	s_addc_u32 s19, s65, s19
	v_lshlrev_b32_e32 v128, 1, v128
	v_max_f32 v124, 0, v124
	v_max_f32 v120, 0, v120
	v_lshl_add_u64 v[158:159], s[18:19], 0, v[128:129]
	v_pk_mul_f32 v[122:123], v[122:123], v[200:201] op_sel_hi:[1,0]
	v_mul_f32_e32 v128, v120, v120
	v_max_f32 v120, 0, v125
	v_max_f32 v121, 0, v121
	v_lshl_or_b32 v148, s24, 8, v152
	v_pk_mul_f32 v[126:127], v[126:127], v[200:201] op_sel_hi:[1,0]
	v_mul_f32_e32 v125, v121, v121
	v_max_f32 v121, 0, v126
	v_max_f32 v122, 0, v122
	v_ashrrev_i32_e32 v149, 31, v148
	v_mul_f32_e32 v126, v122, v122
	v_max_f32 v122, 0, v127
	v_max_f32 v123, 0, v123
	v_lshl_add_u64 v[158:159], v[148:149], 1, v[158:159]
	v_mul_f32_e32 v120, v120, v120
	v_mul_f32_e32 v121, v121, v121
	v_mul_f32_e32 v122, v122, v122
	v_mul_f32_e32 v123, v123, v123
	v_pk_mul_f32 v[116:117], v[116:117], v[200:201] op_sel_hi:[1,0]
	v_pk_mul_f32 v[112:113], v[112:113], v[200:201] op_sel_hi:[1,0]
	v_mul_f32_e32 v124, v124, v124
	v_cvt_pk_bf16_f32 v120, v124, v120
	v_cvt_pk_bf16_f32 v121, v121, v122
	v_cvt_pk_bf16_f32 v122, v128, v125
	v_cvt_pk_bf16_f32 v123, v126, v123
	ds_write_b128 v154, v[120:123]
	ds_read_b128 v[248:251], v187
	s_nop 1
	v_max_f32 v116, 0, v116
	v_max_f32 v112, 0, v112
	v_pk_mul_f32 v[114:115], v[114:115], v[200:201] op_sel_hi:[1,0]
	v_pk_mul_f32 v[118:119], v[118:119], v[200:201] op_sel_hi:[1,0]
	v_mul_f32_e32 v120, v112, v112
	v_max_f32 v112, 0, v117
	v_max_f32 v113, 0, v113
	v_mul_f32_e32 v116, v116, v116
	v_mul_f32_e32 v117, v113, v113
	v_max_f32 v113, 0, v118
	v_max_f32 v114, 0, v114
	v_mul_f32_e32 v112, v112, v112
	v_mul_f32_e32 v118, v114, v114
	v_max_f32 v114, 0, v119
	v_max_f32 v115, 0, v115
	v_mul_f32_e32 v113, v113, v113
	v_mul_f32_e32 v114, v114, v114
	v_mul_f32_e32 v115, v115, v115
	v_cvt_pk_bf16_f32 v112, v116, v112
	v_cvt_pk_bf16_f32 v113, v113, v114
	v_cvt_pk_bf16_f32 v114, v120, v117
	v_cvt_pk_bf16_f32 v115, v118, v115
	ds_write_b128 v154, v[112:115]
	ds_read_b128 v[220:223], v187
	s_nop 1
	s_nop 0
	s_nop 0
	v_or_b32_e32 v112, 16, v150
	s_nop 0
.LBB0_42:
	s_nop 0
	v_pk_mul_f32 v[108:109], v[108:109], v[202:203] op_sel_hi:[1,0]
	v_pk_mul_f32 v[104:105], v[104:105], v[202:203] op_sel_hi:[1,0]
	v_and_b32_e32 v112, 0x7df, v112
	v_max_f32 v108, 0, v108
	v_max_f32 v104, 0, v104
	v_mul_u32_u24_e32 v112, 0x1040, v112
	v_pk_mul_f32 v[106:107], v[106:107], v[202:203] op_sel_hi:[1,0]
	v_mul_f32_e32 v114, v104, v104
	v_max_f32 v104, 0, v109
	v_max_f32 v105, 0, v105
	v_lshlrev_b32_e32 v128, 1, v112
	v_pk_mul_f32 v[110:111], v[110:111], v[202:203] op_sel_hi:[1,0]
	v_mul_f32_e32 v109, v105, v105
	v_max_f32 v105, 0, v110
	v_max_f32 v106, 0, v106
	v_lshl_add_u64 v[112:113], s[18:19], 0, v[128:129]
	v_mul_f32_e32 v110, v106, v106
	v_max_f32 v106, 0, v111
	v_max_f32 v107, 0, v107
	v_lshl_add_u64 v[112:113], v[148:149], 1, v[112:113]
	v_mul_f32_e32 v104, v104, v104
	v_mul_f32_e32 v105, v105, v105
	v_mul_f32_e32 v106, v106, v106
	v_mul_f32_e32 v107, v107, v107
	v_pk_mul_f32 v[100:101], v[100:101], v[202:203] op_sel_hi:[1,0]
	v_pk_mul_f32 v[96:97], v[96:97], v[202:203] op_sel_hi:[1,0]
	v_mul_f32_e32 v108, v108, v108
	v_cvt_pk_bf16_f32 v104, v108, v104
	v_cvt_pk_bf16_f32 v105, v105, v106
	v_cvt_pk_bf16_f32 v106, v114, v109
	v_cvt_pk_bf16_f32 v107, v110, v107
	s_waitcnt lgkmcnt(2)
	global_store_dwordx4 v[158:159], v[248:251], off
	ds_write_b128 v154, v[104:107]
	ds_read_b128 v[248:251], v187
	s_nop 1
	v_max_f32 v100, 0, v100
	v_max_f32 v96, 0, v96
	v_pk_mul_f32 v[98:99], v[98:99], v[202:203] op_sel_hi:[1,0]
	v_pk_mul_f32 v[102:103], v[102:103], v[202:203] op_sel_hi:[1,0]
	v_mul_f32_e32 v104, v96, v96
	v_max_f32 v96, 0, v101
	v_max_f32 v97, 0, v97
	v_mul_f32_e32 v100, v100, v100
	v_mul_f32_e32 v101, v97, v97
	v_max_f32 v97, 0, v102
	v_max_f32 v98, 0, v98
	v_mul_f32_e32 v96, v96, v96
	v_mul_f32_e32 v102, v98, v98
	v_max_f32 v98, 0, v103
	v_mul_f32_e32 v97, v97, v97
	v_mul_f32_e32 v98, v98, v98
	v_max_f32 v99, 0, v99
	v_cvt_pk_bf16_f32 v96, v100, v96
	v_cvt_pk_bf16_f32 v97, v97, v98
	v_cvt_pk_bf16_f32 v98, v104, v101
	v_or_b32_e32 v100, 32, v150
	v_mul_f32_e32 v99, v99, v99
	v_cvt_pk_bf16_f32 v99, v102, v99
	s_waitcnt lgkmcnt(2)
	global_store_dwordx4 v[158:159], v[220:223], off offset:256
	ds_write_b128 v154, v[96:99]
	ds_read_b128 v[220:223], v187
	s_nop 1
	s_nop 0
	s_nop 0
	s_nop 0
	s_nop 0
	s_nop 0
; __device__ __forceinline__ unsigned cvt_pk_bf16(float lo, float hi) { unsigned r; asm volatile("v_cvt_pk_bf16_f32 %0, %1, %2" : "=v"(r) : "v"(lo), "v"(hi)); return r; }
; __device__ __forceinline__ float relu_sq(float x) { float r; asm volatile("v_max_f32 %0, 0, %1" : "=v"(r) : "v"(x)); return r * r; }
;     __device__ __forceinline__ void operator()(const f32x4 (&acc)[2][2][4][2], const Unit& u, int wr, int wc, int fr, int fq) const {
;     ...
;             for (int m = 0; m < 4; ++m) { const int row_ = row0 + ai * HALF + m * 16; bf16_t* rowp = O + (size_t)(row_ >> 11) * gs + (size_t)(row_ & 2047) * ldc + col0; const float sc = rs ? rs[row0 + ai * HALF + m * 16] : 1.f;
; #pragma unroll
;                 for (int bj = 0; bj < 2; ++bj) { f32x4 v0 = acc[ai][bj][m][0] * sc, v1 = acc[ai][bj][m][1] * sc;
;                     if (ACT == 1) {
; #pragma unroll
;                         for (int e = 0; e < 4; ++e) { v0[e] = relu_sq(v0[e]); v1[e] = relu_sq(v1[e]); } }
;                     u32x4 w; w.x = cvt_pk_bf16(v0[0], v0[1]); w.y = cvt_pk_bf16(v0[2], v0[3]); w.z = cvt_pk_bf16(v1[0], v1[1]); w.w = cvt_pk_bf16(v1[2], v1[3]);
;                     *(u32x4*)(rowp + bj * HALF) = w; } }
.LBB0_44:
	v_and_b32_e32 v97, 0x7ef, v100
	s_nop 0
	v_pk_mul_f32 v[92:93], v[92:93], v[204:205] op_sel_hi:[1,0]
	v_pk_mul_f32 v[88:89], v[88:89], v[204:205] op_sel_hi:[1,0]
	v_mul_u32_u24_e32 v97, 0x1040, v97
	v_max_f32 v92, 0, v92
	v_max_f32 v88, 0, v88
	v_lshlrev_b32_e32 v128, 1, v97
	v_pk_mul_f32 v[90:91], v[90:91], v[204:205] op_sel_hi:[1,0]
	v_mul_f32_e32 v97, v88, v88
	v_max_f32 v88, 0, v93
	v_max_f32 v89, 0, v89
	v_pk_mul_f32 v[94:95], v[94:95], v[204:205] op_sel_hi:[1,0]
	v_mul_f32_e32 v93, v89, v89
	v_max_f32 v89, 0, v94
	v_max_f32 v90, 0, v90
	v_lshl_add_u64 v[100:101], s[18:19], 0, v[128:129]
	v_mul_f32_e32 v94, v90, v90
	v_max_f32 v90, 0, v95
	v_max_f32 v91, 0, v91
	v_lshl_add_u64 v[100:101], v[148:149], 1, v[100:101]
	v_mul_f32_e32 v88, v88, v88
	v_mul_f32_e32 v89, v89, v89
	v_mul_f32_e32 v90, v90, v90
	v_mul_f32_e32 v91, v91, v91
	v_pk_mul_f32 v[84:85], v[84:85], v[204:205] op_sel_hi:[1,0]
	v_pk_mul_f32 v[80:81], v[80:81], v[204:205] op_sel_hi:[1,0]
	v_mul_f32_e32 v92, v92, v92
	v_cvt_pk_bf16_f32 v88, v92, v88
	v_cvt_pk_bf16_f32 v89, v89, v90
	v_cvt_pk_bf16_f32 v90, v97, v93
	v_cvt_pk_bf16_f32 v91, v94, v91
	s_waitcnt lgkmcnt(2)
	global_store_dwordx4 v[112:113], v[248:251], off
	ds_write_b128 v154, v[88:91]
	ds_read_b128 v[248:251], v187
	s_nop 1
	v_max_f32 v84, 0, v84
	v_max_f32 v80, 0, v80
	v_pk_mul_f32 v[82:83], v[82:83], v[204:205] op_sel_hi:[1,0]
	v_pk_mul_f32 v[86:87], v[86:87], v[204:205] op_sel_hi:[1,0]
	v_mul_f32_e32 v88, v80, v80
	v_max_f32 v80, 0, v85
	v_max_f32 v81, 0, v81
	v_mul_f32_e32 v84, v84, v84
	v_mul_f32_e32 v85, v81, v81
	v_max_f32 v81, 0, v86
	v_max_f32 v82, 0, v82
	v_mul_f32_e32 v80, v80, v80
	v_mul_f32_e32 v86, v82, v82
	v_max_f32 v82, 0, v87
	v_max_f32 v83, 0, v83
	v_mul_f32_e32 v81, v81, v81
	v_mul_f32_e32 v82, v82, v82
	v_mul_f32_e32 v83, v83, v83
	v_cvt_pk_bf16_f32 v80, v84, v80
	v_cvt_pk_bf16_f32 v81, v81, v82
	v_cvt_pk_bf16_f32 v82, v88, v85
	v_cvt_pk_bf16_f32 v83, v86, v83
	s_waitcnt lgkmcnt(2)
	global_store_dwordx4 v[112:113], v[220:223], off offset:256
	ds_write_b128 v154, v[80:83]
	ds_read_b128 v[220:223], v187
	s_nop 1
	s_nop 0
	s_nop 0
	v_or_b32_e32 v80, 48, v150
	s_nop 0
.LBB0_46:
	s_nop 0
	v_pk_mul_f32 v[76:77], v[76:77], v[206:207] op_sel_hi:[1,0]
	v_pk_mul_f32 v[72:73], v[72:73], v[206:207] op_sel_hi:[1,0]
	v_and_b32_e32 v80, 0x7ff, v80
	v_max_f32 v76, 0, v76
	v_max_f32 v72, 0, v72
	v_mul_u32_u24_e32 v80, 0x1040, v80
	v_pk_mul_f32 v[74:75], v[74:75], v[206:207] op_sel_hi:[1,0]
	v_mul_f32_e32 v82, v72, v72
	v_max_f32 v72, 0, v77
	v_max_f32 v73, 0, v73
	v_lshlrev_b32_e32 v128, 1, v80
	v_pk_mul_f32 v[78:79], v[78:79], v[206:207] op_sel_hi:[1,0]
	v_mul_f32_e32 v77, v73, v73
	v_max_f32 v73, 0, v78
	v_max_f32 v74, 0, v74
	v_lshl_add_u64 v[80:81], s[18:19], 0, v[128:129]
	v_mul_f32_e32 v78, v74, v74
	v_max_f32 v74, 0, v79
	v_max_f32 v75, 0, v75
	v_lshl_add_u64 v[80:81], v[148:149], 1, v[80:81]
	v_mul_f32_e32 v72, v72, v72
	v_mul_f32_e32 v73, v73, v73
	v_mul_f32_e32 v74, v74, v74
	v_mul_f32_e32 v75, v75, v75
	v_pk_mul_f32 v[68:69], v[68:69], v[206:207] op_sel_hi:[1,0]
	v_pk_mul_f32 v[64:65], v[64:65], v[206:207] op_sel_hi:[1,0]
	v_mul_f32_e32 v76, v76, v76
	v_cvt_pk_bf16_f32 v72, v76, v72
	v_cvt_pk_bf16_f32 v73, v73, v74
	v_cvt_pk_bf16_f32 v74, v82, v77
	v_cvt_pk_bf16_f32 v75, v78, v75
	s_waitcnt lgkmcnt(2)
	global_store_dwordx4 v[100:101], v[248:251], off
	ds_write_b128 v154, v[72:75]
	ds_read_b128 v[248:251], v187
	s_nop 1
	v_max_f32 v68, 0, v68
	v_max_f32 v64, 0, v64
	v_pk_mul_f32 v[66:67], v[66:67], v[206:207] op_sel_hi:[1,0]
	v_pk_mul_f32 v[70:71], v[70:71], v[206:207] op_sel_hi:[1,0]
	v_mul_f32_e32 v72, v64, v64
	v_max_f32 v64, 0, v69
	v_max_f32 v65, 0, v65
	v_mul_f32_e32 v68, v68, v68
	v_mul_f32_e32 v69, v65, v65
	v_max_f32 v65, 0, v70
	v_max_f32 v66, 0, v66
	v_mul_f32_e32 v64, v64, v64
	v_mul_f32_e32 v70, v66, v66
	v_max_f32 v66, 0, v71
	v_mul_f32_e32 v65, v65, v65
	v_mul_f32_e32 v66, v66, v66
	v_max_f32 v67, 0, v67
	v_cvt_pk_bf16_f32 v64, v68, v64
	v_cvt_pk_bf16_f32 v65, v65, v66
	v_cvt_pk_bf16_f32 v66, v72, v69
	s_nop 0
	v_mul_f32_e32 v67, v67, v67
	v_cvt_pk_bf16_f32 v67, v70, v67
	s_waitcnt lgkmcnt(2)
	global_store_dwordx4 v[100:101], v[220:223], off offset:256
	ds_write_b128 v154, v[64:67]
	ds_read_b128 v[220:223], v187
	s_nop 1
	v_add_u32_e32 v70, 0x80, v150
	s_nop 0
	s_nop 0
	s_nop 0
.LBB0_48:
	v_ashrrev_i32_e32 v67, 11, v70
	v_mov_b64_e32 v[64:65], s[64:65]
	s_mov_b32 s13, 0x1040000
	v_mad_i64_i32 v[64:65], s[18:19], v67, s13, v[64:65]
	v_and_b32_e32 v67, 0x7cf, v70
	s_nop 0
	v_pk_mul_f32 v[60:61], v[60:61], v[208:209] op_sel_hi:[1,0]
	v_pk_mul_f32 v[56:57], v[56:57], v[208:209] op_sel_hi:[1,0]
	v_mul_u32_u24_e32 v67, 0x1040, v67
	v_max_f32 v60, 0, v60
	v_max_f32 v56, 0, v56
	v_lshlrev_b32_e32 v128, 1, v67
	v_pk_mul_f32 v[58:59], v[58:59], v[208:209] op_sel_hi:[1,0]
	v_mul_f32_e32 v67, v56, v56
	v_max_f32 v56, 0, v61
	v_max_f32 v57, 0, v57
	v_pk_mul_f32 v[62:63], v[62:63], v[208:209] op_sel_hi:[1,0]
	v_mul_f32_e32 v61, v57, v57
	v_max_f32 v57, 0, v62
	v_max_f32 v58, 0, v58
	v_lshl_add_u64 v[70:71], v[64:65], 0, v[128:129]
	v_mul_f32_e32 v62, v58, v58
	v_max_f32 v58, 0, v63
	v_max_f32 v59, 0, v59
	v_lshl_add_u64 v[70:71], v[148:149], 1, v[70:71]
	v_mul_f32_e32 v56, v56, v56
	v_mul_f32_e32 v57, v57, v57
	v_mul_f32_e32 v58, v58, v58
	v_mul_f32_e32 v59, v59, v59
	v_pk_mul_f32 v[52:53], v[52:53], v[208:209] op_sel_hi:[1,0]
	v_pk_mul_f32 v[48:49], v[48:49], v[208:209] op_sel_hi:[1,0]
	v_mul_f32_e32 v60, v60, v60
	v_cvt_pk_bf16_f32 v56, v60, v56
	v_cvt_pk_bf16_f32 v57, v57, v58
	v_cvt_pk_bf16_f32 v58, v67, v61
	v_cvt_pk_bf16_f32 v59, v62, v59
	s_waitcnt lgkmcnt(2)
	global_store_dwordx4 v[80:81], v[248:251], off
	ds_write_b128 v154, v[56:59]
	ds_read_b128 v[248:251], v187
	s_nop 1
	v_max_f32 v52, 0, v52
	v_max_f32 v48, 0, v48
	v_pk_mul_f32 v[50:51], v[50:51], v[208:209] op_sel_hi:[1,0]
	v_pk_mul_f32 v[54:55], v[54:55], v[208:209] op_sel_hi:[1,0]
	v_mul_f32_e32 v56, v48, v48
	v_max_f32 v48, 0, v53
	v_max_f32 v49, 0, v49
	v_mul_f32_e32 v52, v52, v52
	v_mul_f32_e32 v53, v49, v49
	v_max_f32 v49, 0, v54
	v_max_f32 v50, 0, v50
	v_mul_f32_e32 v48, v48, v48
	v_mul_f32_e32 v54, v50, v50
	v_max_f32 v50, 0, v55
	v_max_f32 v51, 0, v51
	v_mul_f32_e32 v49, v49, v49
	v_mul_f32_e32 v50, v50, v50
	v_mul_f32_e32 v51, v51, v51
	v_cvt_pk_bf16_f32 v48, v52, v48
	v_cvt_pk_bf16_f32 v49, v49, v50
	v_cvt_pk_bf16_f32 v50, v56, v53
	v_cvt_pk_bf16_f32 v51, v54, v51
	s_waitcnt lgkmcnt(2)
	global_store_dwordx4 v[80:81], v[220:223], off offset:256
	ds_write_b128 v154, v[48:51]
	ds_read_b128 v[220:223], v187
	s_nop 1
	s_nop 0
	s_nop 0
	v_add_u32_e32 v48, 0x90, v150
	s_nop 0
; __device__ __forceinline__ unsigned cvt_pk_bf16(float lo, float hi) { unsigned r; asm volatile("v_cvt_pk_bf16_f32 %0, %1, %2" : "=v"(r) : "v"(lo), "v"(hi)); return r; }
; __device__ __forceinline__ float relu_sq(float x) { float r; asm volatile("v_max_f32 %0, 0, %1" : "=v"(r) : "v"(x)); return r * r; }
;     __device__ __forceinline__ void operator()(const f32x4 (&acc)[2][2][4][2], const Unit& u, int wr, int wc, int fr, int fq) const {
;     ...
;             for (int m = 0; m < 4; ++m) { const int row_ = row0 + ai * HALF + m * 16; bf16_t* rowp = O + (size_t)(row_ >> 11) * gs + (size_t)(row_ & 2047) * ldc + col0; const float sc = rs ? rs[row0 + ai * HALF + m * 16] : 1.f;
; #pragma unroll
;                 for (int bj = 0; bj < 2; ++bj) { f32x4 v0 = acc[ai][bj][m][0] * sc, v1 = acc[ai][bj][m][1] * sc;
;                     if (ACT == 1) {
; #pragma unroll
;                         for (int e = 0; e < 4; ++e) { v0[e] = relu_sq(v0[e]); v1[e] = relu_sq(v1[e]); } }
;                     u32x4 w; w.x = cvt_pk_bf16(v0[0], v0[1]); w.y = cvt_pk_bf16(v0[2], v0[3]); w.z = cvt_pk_bf16(v1[0], v1[1]); w.w = cvt_pk_bf16(v1[2], v1[3]);
;                     *(u32x4*)(rowp + bj * HALF) = w; } }
.LBB0_50:
	s_nop 0
	v_pk_mul_f32 v[44:45], v[44:45], v[210:211] op_sel_hi:[1,0]
	v_pk_mul_f32 v[40:41], v[40:41], v[210:211] op_sel_hi:[1,0]
	v_and_b32_e32 v48, 0x7df, v48
	v_max_f32 v44, 0, v44
	v_max_f32 v40, 0, v40
	v_mul_u32_u24_e32 v48, 0x1040, v48
	v_pk_mul_f32 v[42:43], v[42:43], v[210:211] op_sel_hi:[1,0]
	v_mul_f32_e32 v50, v40, v40
	v_max_f32 v40, 0, v45
	v_max_f32 v41, 0, v41
	v_lshlrev_b32_e32 v128, 1, v48
	v_pk_mul_f32 v[46:47], v[46:47], v[210:211] op_sel_hi:[1,0]
	v_mul_f32_e32 v45, v41, v41
	v_max_f32 v41, 0, v46
	v_max_f32 v42, 0, v42
	v_lshl_add_u64 v[48:49], v[64:65], 0, v[128:129]
	v_mul_f32_e32 v46, v42, v42
	v_max_f32 v42, 0, v47
	v_max_f32 v43, 0, v43
	v_lshl_add_u64 v[48:49], v[148:149], 1, v[48:49]
	v_mul_f32_e32 v40, v40, v40
	v_mul_f32_e32 v41, v41, v41
	v_mul_f32_e32 v42, v42, v42
	v_mul_f32_e32 v43, v43, v43
	v_pk_mul_f32 v[36:37], v[36:37], v[210:211] op_sel_hi:[1,0]
	v_pk_mul_f32 v[32:33], v[32:33], v[210:211] op_sel_hi:[1,0]
	v_mul_f32_e32 v44, v44, v44
	v_cvt_pk_bf16_f32 v40, v44, v40
	v_cvt_pk_bf16_f32 v41, v41, v42
	v_cvt_pk_bf16_f32 v42, v50, v45
	v_cvt_pk_bf16_f32 v43, v46, v43
	s_waitcnt lgkmcnt(2)
	global_store_dwordx4 v[70:71], v[248:251], off
	ds_write_b128 v154, v[40:43]
	ds_read_b128 v[248:251], v187
	s_nop 1
	v_max_f32 v36, 0, v36
	v_max_f32 v32, 0, v32
	v_pk_mul_f32 v[34:35], v[34:35], v[210:211] op_sel_hi:[1,0]
	v_pk_mul_f32 v[38:39], v[38:39], v[210:211] op_sel_hi:[1,0]
	v_mul_f32_e32 v40, v32, v32
	v_max_f32 v32, 0, v37
	v_max_f32 v33, 0, v33
	v_mul_f32_e32 v36, v36, v36
	v_mul_f32_e32 v37, v33, v33
	v_max_f32 v33, 0, v38
	v_max_f32 v34, 0, v34
	v_mul_f32_e32 v32, v32, v32
	v_mul_f32_e32 v38, v34, v34
	v_max_f32 v34, 0, v39
	v_mul_f32_e32 v33, v33, v33
	v_mul_f32_e32 v34, v34, v34
	v_max_f32 v35, 0, v35
	v_cvt_pk_bf16_f32 v32, v36, v32
	v_cvt_pk_bf16_f32 v33, v33, v34
	v_cvt_pk_bf16_f32 v34, v40, v37
	v_add_u32_e32 v36, 0xa0, v150
	v_mul_f32_e32 v35, v35, v35
	v_cvt_pk_bf16_f32 v35, v38, v35
	s_waitcnt lgkmcnt(2)
	global_store_dwordx4 v[70:71], v[220:223], off offset:256
	ds_write_b128 v154, v[32:35]
	ds_read_b128 v[220:223], v187
	s_nop 1
	s_nop 0
	s_nop 0
	s_nop 0
	s_nop 0
	s_nop 0
.LBB0_52:
	v_and_b32_e32 v33, 0x7ef, v36
	s_nop 0
	v_pk_mul_f32 v[28:29], v[28:29], v[212:213] op_sel_hi:[1,0]
	v_pk_mul_f32 v[24:25], v[24:25], v[212:213] op_sel_hi:[1,0]
	v_mul_u32_u24_e32 v33, 0x1040, v33
	v_max_f32 v28, 0, v28
	v_max_f32 v24, 0, v24
	v_lshlrev_b32_e32 v128, 1, v33
	v_pk_mul_f32 v[26:27], v[26:27], v[212:213] op_sel_hi:[1,0]
	v_mul_f32_e32 v33, v24, v24
	v_max_f32 v24, 0, v29
	v_max_f32 v25, 0, v25
	v_pk_mul_f32 v[30:31], v[30:31], v[212:213] op_sel_hi:[1,0]
	v_mul_f32_e32 v29, v25, v25
	v_max_f32 v25, 0, v30
	v_max_f32 v26, 0, v26
	v_lshl_add_u64 v[36:37], v[64:65], 0, v[128:129]
	v_mul_f32_e32 v30, v26, v26
	v_max_f32 v26, 0, v31
	v_max_f32 v27, 0, v27
	v_lshl_add_u64 v[36:37], v[148:149], 1, v[36:37]
	v_mul_f32_e32 v24, v24, v24
	v_mul_f32_e32 v25, v25, v25
	v_mul_f32_e32 v26, v26, v26
	v_mul_f32_e32 v27, v27, v27
	v_pk_mul_f32 v[20:21], v[20:21], v[212:213] op_sel_hi:[1,0]
	v_pk_mul_f32 v[16:17], v[16:17], v[212:213] op_sel_hi:[1,0]
	v_mul_f32_e32 v28, v28, v28
	v_cvt_pk_bf16_f32 v24, v28, v24
	v_cvt_pk_bf16_f32 v25, v25, v26
	v_cvt_pk_bf16_f32 v26, v33, v29
	v_cvt_pk_bf16_f32 v27, v30, v27
	s_waitcnt lgkmcnt(2)
	global_store_dwordx4 v[48:49], v[248:251], off
	ds_write_b128 v154, v[24:27]
	ds_read_b128 v[248:251], v187
	s_nop 1
	v_max_f32 v20, 0, v20
	v_max_f32 v16, 0, v16
	v_pk_mul_f32 v[18:19], v[18:19], v[212:213] op_sel_hi:[1,0]
	v_pk_mul_f32 v[22:23], v[22:23], v[212:213] op_sel_hi:[1,0]
	v_mul_f32_e32 v24, v16, v16
	v_max_f32 v16, 0, v21
	v_max_f32 v17, 0, v17
	v_mul_f32_e32 v20, v20, v20
	v_mul_f32_e32 v21, v17, v17
	v_max_f32 v17, 0, v22
	v_max_f32 v18, 0, v18
	v_mul_f32_e32 v16, v16, v16
	v_mul_f32_e32 v22, v18, v18
	v_max_f32 v18, 0, v23
	v_max_f32 v19, 0, v19
	v_mul_f32_e32 v17, v17, v17
	v_mul_f32_e32 v18, v18, v18
	v_mul_f32_e32 v19, v19, v19
	v_cvt_pk_bf16_f32 v16, v20, v16
	v_cvt_pk_bf16_f32 v17, v17, v18
	v_cvt_pk_bf16_f32 v18, v24, v21
	v_cvt_pk_bf16_f32 v19, v22, v19
	s_waitcnt lgkmcnt(2)
	global_store_dwordx4 v[48:49], v[220:223], off offset:256
	ds_write_b128 v154, v[16:19]
	ds_read_b128 v[220:223], v187
	s_nop 1
	s_nop 0
	s_nop 0
	v_add_u32_e32 v16, 0xb0, v150
	s_nop 0
.LBB0_54:
	s_nop 0
	v_pk_mul_f32 v[12:13], v[12:13], v[214:215] op_sel_hi:[1,0]
	v_pk_mul_f32 v[8:9], v[8:9], v[214:215] op_sel_hi:[1,0]
	v_and_b32_e32 v16, 0x7ff, v16
	v_max_f32 v12, 0, v12
	v_max_f32 v8, 0, v8
	v_mul_u32_u24_e32 v16, 0x1040, v16
	v_pk_mul_f32 v[10:11], v[10:11], v[214:215] op_sel_hi:[1,0]
	v_mul_f32_e32 v18, v8, v8
	v_max_f32 v8, 0, v13
	v_max_f32 v9, 0, v9
	v_lshlrev_b32_e32 v128, 1, v16
	v_pk_mul_f32 v[14:15], v[14:15], v[214:215] op_sel_hi:[1,0]
	v_mul_f32_e32 v13, v9, v9
	v_max_f32 v9, 0, v14
	v_max_f32 v10, 0, v10
	v_lshl_add_u64 v[16:17], v[64:65], 0, v[128:129]
	v_mul_f32_e32 v14, v10, v10
	v_max_f32 v10, 0, v15
	v_max_f32 v11, 0, v11
	v_lshl_add_u64 v[16:17], v[148:149], 1, v[16:17]
	v_mul_f32_e32 v8, v8, v8
	v_mul_f32_e32 v9, v9, v9
	v_mul_f32_e32 v10, v10, v10
	v_mul_f32_e32 v11, v11, v11
	v_pk_mul_f32 v[4:5], v[4:5], v[214:215] op_sel_hi:[1,0]
	v_pk_mul_f32 v[0:1], v[0:1], v[214:215] op_sel_hi:[1,0]
	v_mul_f32_e32 v12, v12, v12
	v_cvt_pk_bf16_f32 v8, v12, v8
	v_cvt_pk_bf16_f32 v9, v9, v10
	v_cvt_pk_bf16_f32 v10, v18, v13
	v_cvt_pk_bf16_f32 v11, v14, v11
	s_waitcnt lgkmcnt(2)
	global_store_dwordx4 v[36:37], v[248:251], off
	ds_write_b128 v154, v[8:11]
	ds_read_b128 v[248:251], v187
	s_nop 1
	v_max_f32 v4, 0, v4
	v_max_f32 v0, 0, v0
	v_pk_mul_f32 v[2:3], v[2:3], v[214:215] op_sel_hi:[1,0]
	v_pk_mul_f32 v[6:7], v[6:7], v[214:215] op_sel_hi:[1,0]
	v_mul_f32_e32 v8, v0, v0
	v_max_f32 v0, 0, v5
	v_max_f32 v1, 0, v1
	s_andn2_b64 vcc, exec, s[6:7]
	v_mul_f32_e32 v5, v1, v1
	v_max_f32 v1, 0, v6
	v_max_f32 v2, 0, v2
	v_mul_f32_e32 v0, v0, v0
	v_mul_f32_e32 v6, v2, v2
	v_max_f32 v2, 0, v7
	v_max_f32 v3, 0, v3
	v_mul_f32_e32 v1, v1, v1
	v_mul_f32_e32 v2, v2, v2
	v_mul_f32_e32 v3, v3, v3
	s_mov_b64 s[6:7], -1
	v_mul_f32_e32 v4, v4, v4
	v_cvt_pk_bf16_f32 v0, v4, v0
	v_cvt_pk_bf16_f32 v1, v1, v2
	v_cvt_pk_bf16_f32 v2, v8, v5
	v_cvt_pk_bf16_f32 v3, v6, v3
	s_waitcnt lgkmcnt(2)
	global_store_dwordx4 v[36:37], v[220:223], off offset:256
	s_waitcnt lgkmcnt(0)
	global_store_dwordx4 v[16:17], v[248:251], off
	ds_write_b128 v154, v[0:3]
	ds_read_b128 v[220:223], v187
	s_nop 1
	s_waitcnt lgkmcnt(0)
	global_store_dwordx4 v[16:17], v[220:223], off offset:256
	s_cbranch_vccnz .LBB0_27
	s_andn2_b64 vcc, exec, s[4:5]
	s_cbranch_vccnz .LBB0_26
	s_barrier
	s_branch .LBB0_26

; __device__ __forceinline__ unsigned cvt_pk_bf16(float lo, float hi) { unsigned r; asm volatile("v_cvt_pk_bf16_f32 %0, %1, %2" : "=v"(r) : "v"(lo), "v"(hi)); return r; }
; __device__ __forceinline__ float relu_sq(float x) { float r; asm volatile("v_max_f32 %0, 0, %1" : "=v"(r) : "v"(x)); return r * r; }
;     __device__ __forceinline__ void operator()(const f32x4 (&acc)[2][2][4][2], const Unit& u, int wr, int wc, int fr, int fq) const {
;     ...
;             for (int m = 0; m < 4; ++m) { const int row_ = row0 + ai * HALF + m * 16; bf16_t* rowp = O + (size_t)(row_ >> 11) * gs + (size_t)(row_ & 2047) * ldc + col0; const float sc = rs ? rs[row0 + ai * HALF + m * 16] : 1.f;
; #pragma unroll
;                 for (int bj = 0; bj < 2; ++bj) { f32x4 v0 = acc[ai][bj][m][0] * sc, v1 = acc[ai][bj][m][1] * sc;
;                     if (ACT == 1) {
; #pragma unroll
;                         for (int e = 0; e < 4; ++e) { v0[e] = relu_sq(v0[e]); v1[e] = relu_sq(v1[e]); } }
;                     u32x4 w; w.x = cvt_pk_bf16(v0[0], v0[1]); w.y = cvt_pk_bf16(v0[2], v0[3]); w.z = cvt_pk_bf16(v1[0], v1[1]); w.w = cvt_pk_bf16(v1[2], v1[3]);
;                     *(u32x4*)(rowp + bj * HALF) = w; } }
.LBB0_473:
	v_bitop3_b32 v128, v150, v184, v150 bitop3:0xc8
	s_ashr_i32 s41, s41, 11
	s_mul_hi_i32 s43, s26, s41
	s_mul_i32 s42, s26, s41
	s_lshl_b64 s[42:43], s[42:43], 1
	v_lshl_or_b32 v148, s88, 8, v152
	s_add_u32 s88, s12, s42
	v_mul_u32_u24_e32 v128, s39, v128
	s_addc_u32 s89, s13, s43
	v_lshlrev_b32_e32 v128, 1, v128
	v_ashrrev_i32_e32 v149, 31, v148
	v_lshl_add_u64 v[158:159], s[88:89], 0, v[128:129]
	v_lshl_add_u64 v[158:159], v[148:149], 1, v[158:159]
	s_nop 0
	v_pk_mul_f32 v[126:127], v[126:127], v[200:201] op_sel_hi:[1,0]
	v_pk_mul_f32 v[124:125], v[124:125], v[200:201] op_sel_hi:[1,0]
	v_pk_mul_f32 v[160:161], v[122:123], v[200:201] op_sel_hi:[1,0]
	v_pk_mul_f32 v[122:123], v[120:121], v[200:201] op_sel_hi:[1,0]
	v_cvt_pk_bf16_f32 v120, v124, v125
	v_cvt_pk_bf16_f32 v121, v126, v127
	s_nop 0
	v_cvt_pk_bf16_f32 v122, v122, v123
	v_cvt_pk_bf16_f32 v123, v160, v161
	ds_write_b128 v154, v[120:123]
	ds_read_b128 v[216:219], v187
	s_nop 1
	v_pk_mul_f32 v[118:119], v[118:119], v[200:201] op_sel_hi:[1,0]
	v_pk_mul_f32 v[116:117], v[116:117], v[200:201] op_sel_hi:[1,0]
	v_pk_mul_f32 v[120:121], v[114:115], v[200:201] op_sel_hi:[1,0]
	v_pk_mul_f32 v[114:115], v[112:113], v[200:201] op_sel_hi:[1,0]
	v_cvt_pk_bf16_f32 v112, v116, v117
	v_cvt_pk_bf16_f32 v113, v118, v119
	s_nop 0
	v_cvt_pk_bf16_f32 v114, v114, v115
	v_cvt_pk_bf16_f32 v115, v120, v121
	ds_write_b128 v154, v[112:115]
	ds_read_b128 v[220:223], v187
	s_nop 1
	s_nop 0
.LBB0_475:
	s_movk_i32 s41, 0x7df
	v_bitop3_b32 v112, v150, s41, 16 bitop3:0xc8
	v_mul_u32_u24_e32 v112, s39, v112
	v_lshlrev_b32_e32 v128, 1, v112
	v_lshl_add_u64 v[112:113], s[88:89], 0, v[128:129]
	v_lshl_add_u64 v[112:113], v[148:149], 1, v[112:113]
	s_nop 0
	v_pk_mul_f32 v[110:111], v[110:111], v[202:203] op_sel_hi:[1,0]
	v_pk_mul_f32 v[108:109], v[108:109], v[202:203] op_sel_hi:[1,0]
	v_pk_mul_f32 v[114:115], v[106:107], v[202:203] op_sel_hi:[1,0]
	v_pk_mul_f32 v[106:107], v[104:105], v[202:203] op_sel_hi:[1,0]
	v_cvt_pk_bf16_f32 v104, v108, v109
	v_cvt_pk_bf16_f32 v105, v110, v111
	v_pk_mul_f32 v[102:103], v[102:103], v[202:203] op_sel_hi:[1,0]
	v_cvt_pk_bf16_f32 v106, v106, v107
	v_cvt_pk_bf16_f32 v107, v114, v115
	s_waitcnt lgkmcnt(2)
	global_store_dwordx4 v[158:159], v[216:219], off
	ds_write_b128 v154, v[104:107]
	ds_read_b128 v[216:219], v187
	s_nop 1
	v_pk_mul_f32 v[100:101], v[100:101], v[202:203] op_sel_hi:[1,0]
	s_nop 0
	v_pk_mul_f32 v[104:105], v[98:99], v[202:203] op_sel_hi:[1,0]
	v_pk_mul_f32 v[98:99], v[96:97], v[202:203] op_sel_hi:[1,0]
	v_cvt_pk_bf16_f32 v96, v100, v101
	v_cvt_pk_bf16_f32 v97, v102, v103
	s_nop 0
	v_cvt_pk_bf16_f32 v98, v98, v99
	v_cvt_pk_bf16_f32 v99, v104, v105
	s_waitcnt lgkmcnt(2)
	global_store_dwordx4 v[158:159], v[220:223], off offset:256
	ds_write_b128 v154, v[96:99]
	ds_read_b128 v[220:223], v187
	s_nop 1
	s_nop 1
	s_nop 0
	s_nop 0
	s_nop 0
.LBB0_477:
	v_bitop3_b32 v97, v150, s51, 32 bitop3:0xc8
	v_mul_u32_u24_e32 v97, s39, v97
	v_lshlrev_b32_e32 v128, 1, v97
	v_lshl_add_u64 v[100:101], s[88:89], 0, v[128:129]
	v_lshl_add_u64 v[100:101], v[148:149], 1, v[100:101]
	s_nop 0
	v_pk_mul_f32 v[94:95], v[94:95], v[204:205] op_sel_hi:[1,0]
	v_pk_mul_f32 v[92:93], v[92:93], v[204:205] op_sel_hi:[1,0]
	v_pk_mul_f32 v[102:103], v[90:91], v[204:205] op_sel_hi:[1,0]
	v_pk_mul_f32 v[90:91], v[88:89], v[204:205] op_sel_hi:[1,0]
	v_cvt_pk_bf16_f32 v88, v92, v93
	v_cvt_pk_bf16_f32 v89, v94, v95
	s_nop 0
	v_cvt_pk_bf16_f32 v90, v90, v91
	v_cvt_pk_bf16_f32 v91, v102, v103
	s_waitcnt lgkmcnt(2)
	global_store_dwordx4 v[112:113], v[216:219], off
	ds_write_b128 v154, v[88:91]
	ds_read_b128 v[216:219], v187
	s_nop 1
	v_pk_mul_f32 v[86:87], v[86:87], v[204:205] op_sel_hi:[1,0]
	v_pk_mul_f32 v[84:85], v[84:85], v[204:205] op_sel_hi:[1,0]
	v_pk_mul_f32 v[88:89], v[82:83], v[204:205] op_sel_hi:[1,0]
	v_pk_mul_f32 v[82:83], v[80:81], v[204:205] op_sel_hi:[1,0]
	v_cvt_pk_bf16_f32 v80, v84, v85
	v_cvt_pk_bf16_f32 v81, v86, v87
	s_nop 0
	v_cvt_pk_bf16_f32 v82, v82, v83
	v_cvt_pk_bf16_f32 v83, v88, v89
	s_waitcnt lgkmcnt(2)
	global_store_dwordx4 v[112:113], v[220:223], off offset:256
	ds_write_b128 v154, v[80:83]
	ds_read_b128 v[220:223], v187
	s_nop 1
	s_nop 0
.LBB0_479:
	s_movk_i32 s41, 0x7ff
	v_bitop3_b32 v80, v150, s41, 48 bitop3:0xc8
	v_mul_u32_u24_e32 v80, s39, v80
	v_lshlrev_b32_e32 v128, 1, v80
	v_lshl_add_u64 v[80:81], s[88:89], 0, v[128:129]
	v_lshl_add_u64 v[80:81], v[148:149], 1, v[80:81]
	s_nop 0
	v_pk_mul_f32 v[78:79], v[78:79], v[206:207] op_sel_hi:[1,0]
	v_pk_mul_f32 v[76:77], v[76:77], v[206:207] op_sel_hi:[1,0]
	v_pk_mul_f32 v[82:83], v[74:75], v[206:207] op_sel_hi:[1,0]
	v_pk_mul_f32 v[74:75], v[72:73], v[206:207] op_sel_hi:[1,0]
	v_cvt_pk_bf16_f32 v72, v76, v77
	v_cvt_pk_bf16_f32 v73, v78, v79
	v_pk_mul_f32 v[70:71], v[70:71], v[206:207] op_sel_hi:[1,0]
	v_cvt_pk_bf16_f32 v74, v74, v75
	v_cvt_pk_bf16_f32 v75, v82, v83
	s_waitcnt lgkmcnt(2)
	global_store_dwordx4 v[100:101], v[216:219], off
	ds_write_b128 v154, v[72:75]
	ds_read_b128 v[216:219], v187
	s_nop 1
	v_pk_mul_f32 v[68:69], v[68:69], v[206:207] op_sel_hi:[1,0]
	s_nop 0
	v_pk_mul_f32 v[72:73], v[66:67], v[206:207] op_sel_hi:[1,0]
	v_pk_mul_f32 v[66:67], v[64:65], v[206:207] op_sel_hi:[1,0]
	v_cvt_pk_bf16_f32 v64, v68, v69
	v_cvt_pk_bf16_f32 v65, v70, v71
	s_nop 0
	v_cvt_pk_bf16_f32 v66, v66, v67
	v_cvt_pk_bf16_f32 v67, v72, v73
	s_waitcnt lgkmcnt(2)
	global_store_dwordx4 v[100:101], v[220:223], off offset:256
	ds_write_b128 v154, v[64:67]
	ds_read_b128 v[220:223], v187
	s_nop 1
	s_nop 1
	v_add_u32_e32 v64, 0x80, v150
	s_nop 0
	s_nop 0
; __device__ __forceinline__ unsigned cvt_pk_bf16(float lo, float hi) { unsigned r; asm volatile("v_cvt_pk_bf16_f32 %0, %1, %2" : "=v"(r) : "v"(lo), "v"(hi)); return r; }
; __device__ __forceinline__ float relu_sq(float x) { float r; asm volatile("v_max_f32 %0, 0, %1" : "=v"(r) : "v"(x)); return r * r; }
;     __device__ __forceinline__ void operator()(const f32x4 (&acc)[2][2][4][2], const Unit& u, int wr, int wc, int fr, int fq) const {
;     ...
;             for (int m = 0; m < 4; ++m) { const int row_ = row0 + ai * HALF + m * 16; bf16_t* rowp = O + (size_t)(row_ >> 11) * gs + (size_t)(row_ & 2047) * ldc + col0; const float sc = rs ? rs[row0 + ai * HALF + m * 16] : 1.f;
; #pragma unroll
;                 for (int bj = 0; bj < 2; ++bj) { f32x4 v0 = acc[ai][bj][m][0] * sc, v1 = acc[ai][bj][m][1] * sc;
;                     if (ACT == 1) {
; #pragma unroll
;                         for (int e = 0; e < 4; ++e) { v0[e] = relu_sq(v0[e]); v1[e] = relu_sq(v1[e]); } }
;                     u32x4 w; w.x = cvt_pk_bf16(v0[0], v0[1]); w.y = cvt_pk_bf16(v0[2], v0[3]); w.z = cvt_pk_bf16(v1[0], v1[1]); w.w = cvt_pk_bf16(v1[2], v1[3]);
;                     *(u32x4*)(rowp + bj * HALF) = w; } }
.LBB0_481:
	v_and_b32_e32 v67, 0x7cf, v64
	v_ashrrev_i32_e32 v64, 11, v64
	v_mad_i64_i32 v[64:65], s[42:43], s26, v64, 0
	v_mul_u32_u24_e32 v67, s39, v67
	v_lshl_add_u64 v[64:65], v[64:65], 1, s[12:13]
	v_lshlrev_b32_e32 v128, 1, v67
	v_lshl_add_u64 v[70:71], v[64:65], 0, v[128:129]
	v_lshl_add_u64 v[70:71], v[148:149], 1, v[70:71]
	s_nop 0
	v_pk_mul_f32 v[62:63], v[62:63], v[208:209] op_sel_hi:[1,0]
	v_pk_mul_f32 v[60:61], v[60:61], v[208:209] op_sel_hi:[1,0]
	v_pk_mul_f32 v[72:73], v[58:59], v[208:209] op_sel_hi:[1,0]
	v_pk_mul_f32 v[58:59], v[56:57], v[208:209] op_sel_hi:[1,0]
	v_cvt_pk_bf16_f32 v56, v60, v61
	v_cvt_pk_bf16_f32 v57, v62, v63
	v_pk_mul_f32 v[52:53], v[52:53], v[208:209] op_sel_hi:[1,0]
	v_cvt_pk_bf16_f32 v58, v58, v59
	v_cvt_pk_bf16_f32 v59, v72, v73
	s_waitcnt lgkmcnt(2)
	global_store_dwordx4 v[80:81], v[216:219], off
	ds_write_b128 v154, v[56:59]
	ds_read_b128 v[216:219], v187
	s_nop 1
	v_pk_mul_f32 v[54:55], v[54:55], v[208:209] op_sel_hi:[1,0]
	s_nop 0
	v_pk_mul_f32 v[56:57], v[50:51], v[208:209] op_sel_hi:[1,0]
	v_pk_mul_f32 v[50:51], v[48:49], v[208:209] op_sel_hi:[1,0]
	v_cvt_pk_bf16_f32 v48, v52, v53
	v_cvt_pk_bf16_f32 v49, v54, v55
	s_nop 0
	v_cvt_pk_bf16_f32 v50, v50, v51
	v_cvt_pk_bf16_f32 v51, v56, v57
	s_waitcnt lgkmcnt(2)
	global_store_dwordx4 v[80:81], v[220:223], off offset:256
	ds_write_b128 v154, v[48:51]
	ds_read_b128 v[220:223], v187
	s_nop 1
	s_nop 1
	v_add_u32_e32 v48, 0x90, v150
	s_nop 0
.LBB0_483:
	v_and_b32_e32 v48, 0x7df, v48
	v_mul_u32_u24_e32 v48, s39, v48
	v_lshlrev_b32_e32 v128, 1, v48
	v_lshl_add_u64 v[48:49], v[64:65], 0, v[128:129]
	v_lshl_add_u64 v[48:49], v[148:149], 1, v[48:49]
	s_nop 0
	v_pk_mul_f32 v[46:47], v[46:47], v[210:211] op_sel_hi:[1,0]
	v_pk_mul_f32 v[44:45], v[44:45], v[210:211] op_sel_hi:[1,0]
	v_pk_mul_f32 v[50:51], v[42:43], v[210:211] op_sel_hi:[1,0]
	v_pk_mul_f32 v[42:43], v[40:41], v[210:211] op_sel_hi:[1,0]
	v_cvt_pk_bf16_f32 v40, v44, v45
	v_cvt_pk_bf16_f32 v41, v46, v47
	v_pk_mul_f32 v[38:39], v[38:39], v[210:211] op_sel_hi:[1,0]
	v_cvt_pk_bf16_f32 v42, v42, v43
	v_cvt_pk_bf16_f32 v43, v50, v51
	s_waitcnt lgkmcnt(2)
	global_store_dwordx4 v[70:71], v[216:219], off
	ds_write_b128 v154, v[40:43]
	ds_read_b128 v[216:219], v187
	s_nop 1
	v_pk_mul_f32 v[36:37], v[36:37], v[210:211] op_sel_hi:[1,0]
	s_nop 0
	v_pk_mul_f32 v[40:41], v[34:35], v[210:211] op_sel_hi:[1,0]
	v_pk_mul_f32 v[34:35], v[32:33], v[210:211] op_sel_hi:[1,0]
	v_cvt_pk_bf16_f32 v32, v36, v37
	v_cvt_pk_bf16_f32 v33, v38, v39
	v_add_u32_e32 v36, 0xa0, v150
	v_cvt_pk_bf16_f32 v34, v34, v35
	v_cvt_pk_bf16_f32 v35, v40, v41
	s_waitcnt lgkmcnt(2)
	global_store_dwordx4 v[70:71], v[220:223], off offset:256
	ds_write_b128 v154, v[32:35]
	ds_read_b128 v[220:223], v187
	s_nop 1
	s_nop 1
	s_nop 0
	s_nop 0
	s_nop 0
.LBB0_485:
	v_and_b32_e32 v33, 0x7ef, v36
	v_mul_u32_u24_e32 v33, s39, v33
	v_lshlrev_b32_e32 v128, 1, v33
	v_lshl_add_u64 v[36:37], v[64:65], 0, v[128:129]
	v_lshl_add_u64 v[36:37], v[148:149], 1, v[36:37]
	s_nop 0
	v_pk_mul_f32 v[30:31], v[30:31], v[212:213] op_sel_hi:[1,0]
	v_pk_mul_f32 v[28:29], v[28:29], v[212:213] op_sel_hi:[1,0]
	v_pk_mul_f32 v[38:39], v[26:27], v[212:213] op_sel_hi:[1,0]
	v_pk_mul_f32 v[26:27], v[24:25], v[212:213] op_sel_hi:[1,0]
	v_cvt_pk_bf16_f32 v24, v28, v29
	v_cvt_pk_bf16_f32 v25, v30, v31
	v_pk_mul_f32 v[20:21], v[20:21], v[212:213] op_sel_hi:[1,0]
	v_cvt_pk_bf16_f32 v26, v26, v27
	v_cvt_pk_bf16_f32 v27, v38, v39
	s_waitcnt lgkmcnt(2)
	global_store_dwordx4 v[48:49], v[216:219], off
	ds_write_b128 v154, v[24:27]
	ds_read_b128 v[216:219], v187
	s_nop 1
	v_pk_mul_f32 v[22:23], v[22:23], v[212:213] op_sel_hi:[1,0]
	s_nop 0
	v_pk_mul_f32 v[24:25], v[18:19], v[212:213] op_sel_hi:[1,0]
	v_pk_mul_f32 v[18:19], v[16:17], v[212:213] op_sel_hi:[1,0]
	v_cvt_pk_bf16_f32 v16, v20, v21
	v_cvt_pk_bf16_f32 v17, v22, v23
	s_nop 0
	v_cvt_pk_bf16_f32 v18, v18, v19
	v_cvt_pk_bf16_f32 v19, v24, v25
	s_waitcnt lgkmcnt(2)
	global_store_dwordx4 v[48:49], v[220:223], off offset:256
	ds_write_b128 v154, v[16:19]
	ds_read_b128 v[220:223], v187
	s_nop 1
	s_nop 1
	v_add_u32_e32 v16, 0xb0, v150
	s_nop 0
.LBB0_487:
	v_and_b32_e32 v16, 0x7ff, v16
	v_mul_u32_u24_e32 v16, s39, v16
	v_lshlrev_b32_e32 v128, 1, v16
	v_lshl_add_u64 v[16:17], v[64:65], 0, v[128:129]
	v_lshl_add_u64 v[16:17], v[148:149], 1, v[16:17]
	s_nop 0
	v_pk_mul_f32 v[14:15], v[14:15], v[214:215] op_sel_hi:[1,0]
	v_pk_mul_f32 v[12:13], v[12:13], v[214:215] op_sel_hi:[1,0]
	v_pk_mul_f32 v[18:19], v[10:11], v[214:215] op_sel_hi:[1,0]
	v_pk_mul_f32 v[10:11], v[8:9], v[214:215] op_sel_hi:[1,0]
	v_cvt_pk_bf16_f32 v8, v12, v13
	v_cvt_pk_bf16_f32 v9, v14, v15
	s_and_b64 vcc, exec, s[6:7]
	v_cvt_pk_bf16_f32 v10, v10, v11
	v_cvt_pk_bf16_f32 v11, v18, v19
	s_waitcnt lgkmcnt(2)
	global_store_dwordx4 v[36:37], v[216:219], off
	ds_write_b128 v154, v[8:11]
	ds_read_b128 v[216:219], v187
	s_nop 1
	s_mov_b64 s[6:7], -1
	v_pk_mul_f32 v[6:7], v[6:7], v[214:215] op_sel_hi:[1,0]
	v_pk_mul_f32 v[8:9], v[2:3], v[214:215] op_sel_hi:[1,0]
	v_pk_mul_f32 v[2:3], v[0:1], v[214:215] op_sel_hi:[1,0]
	v_pk_mul_f32 v[4:5], v[4:5], v[214:215] op_sel_hi:[1,0]
	s_nop 0
	v_cvt_pk_bf16_f32 v0, v4, v5
	v_cvt_pk_bf16_f32 v1, v6, v7
	v_cvt_pk_bf16_f32 v2, v2, v3
	v_cvt_pk_bf16_f32 v3, v8, v9
	s_waitcnt lgkmcnt(2)
	global_store_dwordx4 v[36:37], v[220:223], off offset:256
	s_waitcnt lgkmcnt(0)
	global_store_dwordx4 v[16:17], v[216:219], off
	ds_write_b128 v154, v[0:3]
	ds_read_b128 v[220:223], v187
	s_nop 1
	s_waitcnt lgkmcnt(0)
	global_store_dwordx4 v[16:17], v[220:223], off offset:256
	s_cbranch_vccnz .LBB0_458
	s_andn2_b64 vcc, exec, s[18:19]
	s_cbranch_vccnz .LBB0_457
	s_barrier
	s_branch .LBB0_457
